# DIL unit: L2-warming touches of previous-group output rows and lse beside the Q loads
# baseline (speedup 1.0000x reference)
; #define LAS __attribute__((address_space(3)))
; __device__ __forceinline__ void glds16(const void* gsrc, LAS unsigned char* dst_uniform) { __builtin_amdgcn_global_load_lds((const unsigned*)gsrc, (LAS unsigned*)dst_uniform, 16, 0, 0); }
; #define ATT_SYNC() do { asm volatile("s_waitcnt vmcnt(0) lgkmcnt(0)" ::: "memory"); __syncthreads(); } while (0)
; __device__ __forceinline__ void dil_unit(LAS unsigned char* lds, const LAS float* btab, const bf16_t* QKV, int gi, int ldil, int b, int h, int r, int ub, bf16_t* AO, float* lseacc, const int tid) {
;     ...
; #pragma unroll 4
;     for (int ii = 0; ii < 12; ++ii) { const int i = wid * 12 + ii, kk = 4 * i + (lane >> 4), c = (lane & 15) ^ (kk & 15); int ki = k0 + kk; ki = ki < 0 ? 0 : (ki >= sub_len ? sub_len - 1 : ki);
;         glds16(base + (tokb + ((size_t)ki << ldil)) * 3072 + 1024 + c * 8, lds + i * 1024); }
;     const int qi = ub * 256 + wid * 32 + r32; const size_t qtok = tokb + ((size_t)qi << ldil);
;     bf16x8 qf[8]; { const bf16_t* qp = base + qtok * 3072 + hi * 8;
; #pragma unroll
;         for (int s = 0; s < 8; ++s) qf[s] = *(const bf16x8*)(qp + 16 * s); }
;     ATT_SYNC();
;     f32x16 S[5];
;     int r15 = r32 & 15; asm volatile("" : "+v"(r15));
; #pragma unroll
;     for (int t = 0; t < 5; ++t) { f32x16 acc = {}; const lds_cptr kp = (lds_cptr)lds + (32 * wid + 32 * t + r32) * 256;
; #pragma unroll
;         for (int s = 0; s < 8; ++s) { const bf16x8 kf = *(const LAS bf16x8*)(kp + (((2 * s + hi) ^ r15) << 4)); acc = __builtin_amdgcn_mfma_f32_32x32x16_bf16(kf, qf[s], acc, 0, 0, 0); }
;         S[t] = acc; }
;     ATT_SYNC();
.LBB0_663:
	v_add_u32_e32 v10, s25, v2
	v_subrev_u32_e32 v0, 64, v10
	s_waitcnt lgkmcnt(0)
	v_min_i32_e32 v1, s18, v0
	v_cmp_lt_i32_e32 vcc, -1, v0
	v_add_u32_e32 v8, s25, v3
	v_xor_b32_e32 v9, v8, v237
	v_cndmask_b32_e32 v0, 0, v1, vcc
	v_ashrrev_i32_e32 v1, 31, v0
	v_lshlrev_b64 v[0:1], s12, v[0:1]
	v_lshl_add_u64 v[4:5], v[0:1], 0, s[0:1]
	v_mov_b64_e32 v[0:1], s[2:3]
	v_mad_u64_u32 v[6:7], s[30:31], v4, s36, v[0:1]
	v_mov_b32_e32 v4, v7
	v_mad_u64_u32 v[4:5], s[30:31], v5, s36, v[4:5]
	v_mov_b32_e32 v7, v4
	v_lshlrev_b32_e32 v4, 4, v9
	v_and_b32_e32 v208, 0xf0, v4
	v_lshl_add_u64 v[4:5], v[6:7], 0, v[208:209]
	v_lshl_add_u64 v[4:5], v[4:5], 0, s[38:39]
	s_mov_b32 m0, s28
	s_add_i32 s25, s25, 16
	global_load_lds_dwordx4 v[4:5], off
	v_add_u32_e32 v4, 4, v8
	v_xor_b32_e32 v9, v4, v237
	v_subrev_u32_e32 v4, 60, v10
	v_min_i32_e32 v5, s18, v4
	v_cmp_lt_i32_e32 vcc, -1, v4
	s_add_i32 m0, s28, 0x400
	s_nop 0
	v_cndmask_b32_e32 v4, 0, v5, vcc
	v_ashrrev_i32_e32 v5, 31, v4
	v_lshlrev_b64 v[4:5], s12, v[4:5]
	v_lshl_add_u64 v[4:5], v[4:5], 0, s[0:1]
	v_mad_u64_u32 v[6:7], s[30:31], v4, s36, v[0:1]
	v_mov_b32_e32 v4, v7
	v_mad_u64_u32 v[4:5], s[30:31], v5, s36, v[4:5]
	v_mov_b32_e32 v7, v4
	v_lshlrev_b32_e32 v4, 4, v9
	v_and_b32_e32 v208, 0xf0, v4
	v_lshl_add_u64 v[4:5], v[6:7], 0, v[208:209]
	v_lshl_add_u64 v[4:5], v[4:5], 0, s[38:39]
	global_load_lds_dwordx4 v[4:5], off
	v_add_u32_e32 v4, 8, v8
	v_xor_b32_e32 v9, v4, v237
	v_subrev_u32_e32 v4, 56, v10
	v_min_i32_e32 v5, s18, v4
	v_cmp_lt_i32_e32 vcc, -1, v4
	s_add_i32 m0, s28, 0x800
	s_nop 0
	v_cndmask_b32_e32 v4, 0, v5, vcc
	v_ashrrev_i32_e32 v5, 31, v4
	v_lshlrev_b64 v[4:5], s12, v[4:5]
	v_lshl_add_u64 v[4:5], v[4:5], 0, s[0:1]
	v_mad_u64_u32 v[6:7], s[30:31], v4, s36, v[0:1]
	v_mov_b32_e32 v4, v7
	v_mad_u64_u32 v[4:5], s[30:31], v5, s36, v[4:5]
	v_mov_b32_e32 v7, v4
	v_lshlrev_b32_e32 v4, 4, v9
	v_and_b32_e32 v208, 0xf0, v4
	v_lshl_add_u64 v[4:5], v[6:7], 0, v[208:209]
	v_lshl_add_u64 v[4:5], v[4:5], 0, s[38:39]
	global_load_lds_dwordx4 v[4:5], off
	v_add_u32_e32 v4, 12, v8
	v_xor_b32_e32 v6, v4, v237
	v_subrev_u32_e32 v4, 52, v10
	v_min_i32_e32 v5, s18, v4
	v_cmp_lt_i32_e32 vcc, -1, v4
	s_add_i32 m0, s28, 0xc00
	s_addk_i32 s28, 0x1000
	v_cndmask_b32_e32 v4, 0, v5, vcc
	v_ashrrev_i32_e32 v5, 31, v4
	v_lshlrev_b64 v[4:5], s12, v[4:5]
	v_lshl_add_u64 v[4:5], v[4:5], 0, s[0:1]
	v_mad_u64_u32 v[0:1], s[30:31], v4, s36, v[0:1]
	v_mov_b32_e32 v4, v1
	v_mad_u64_u32 v[4:5], s[30:31], v5, s36, v[4:5]
	v_mov_b32_e32 v1, v4
	v_lshlrev_b32_e32 v4, 4, v6
	v_and_b32_e32 v208, 0xf0, v4
	v_lshl_add_u64 v[0:1], v[0:1], 0, v[208:209]
	v_lshl_add_u64 v[0:1], v[0:1], 0, s[38:39]
	global_load_lds_dwordx4 v[0:1], off
	s_cmp_eq_u32 s25, 48
	s_cbranch_scc0 .LBB0_663
	s_lshl_b32 s28, s20, 5
	v_and_b32_e32 v240, 31, v237
	s_add_i32 s25, s28, s27
	v_or_b32_e32 v0, s25, v240
	v_ashrrev_i32_e32 v1, 31, v0
	v_lshlrev_b64 v[0:1], s12, v[0:1]
	v_lshl_add_u64 v[218:219], v[0:1], 0, s[0:1]
	v_mov_b64_e32 v[0:1], s[2:3]
	v_mad_u64_u32 v[0:1], s[30:31], v218, s36, v[0:1]
	v_mov_b32_e32 v2, v1
	v_lshrrev_b32_e32 v239, 5, v238
	v_mad_u64_u32 v[2:3], s[30:31], v219, s36, v[2:3]
	v_mov_b32_e32 v1, v2
	v_lshlrev_b32_e32 v220, 4, v239
	v_mov_b32_e32 v221, v209
	v_lshl_add_u64 v[4:5], v[0:1], 0, v[220:221]
	global_load_dwordx4 v[0:3], v[4:5], off
	global_load_dwordx4 v[80:83], v[4:5], off offset:32
	global_load_dwordx4 v[84:87], v[4:5], off offset:64
	global_load_dwordx4 v[88:91], v[4:5], off offset:96
	global_load_dwordx4 v[92:95], v[4:5], off offset:128
	global_load_dwordx4 v[96:99], v[4:5], off offset:160
	global_load_dwordx4 v[100:103], v[4:5], off offset:192
	global_load_dwordx4 v[104:107], v[4:5], off offset:224
	s_lshl_b32 s29, s20, 13
	v_and_b32_e32 v4, 15, v237
	s_add_i32 s29, s29, 0
	v_lshlrev_b64 v[110:111], 11, v[218:219]
	v_lshl_add_u64 v[110:111], s[6:7], 0, v[110:111]
	global_load_dword v112, v[110:111], off
	global_load_dword v112, v[110:111], off offset:128
	v_lshlrev_b64 v[110:111], 5, v[218:219]
	v_lshl_add_u64 v[110:111], s[8:9], 0, v[110:111]
	global_load_dword v112, v[110:111], off
	v_cmp_gt_i32_e32 vcc, 0xc0, v237
	s_nop 1
	s_and_saveexec_b64 vcc, vcc
	s_waitcnt vmcnt(0)
	ds_write_b32 v109, v108
	s_mov_b64 exec, vcc
	s_waitcnt vmcnt(0) lgkmcnt(0)
	s_waitcnt vmcnt(0) lgkmcnt(0)
	s_barrier
	v_lshl_add_u32 v6, v240, 8, s29
	v_xor_b32_e32 v5, v4, v239
	v_lshl_add_u32 v52, v5, 4, v6
	v_bitop3_b32 v5, v4, v239, 2 bitop3:0x1e
	v_lshl_add_u32 v53, v5, 4, v6
	v_bitop3_b32 v5, v4, v239, 4 bitop3:0x1e
	v_lshl_add_u32 v56, v5, 4, v6
	v_bitop3_b32 v5, v4, v239, 6 bitop3:0x1e
	v_lshl_add_u32 v57, v5, 4, v6
	v_bitop3_b32 v5, v4, v239, 8 bitop3:0x1e
	v_lshl_add_u32 v60, v5, 4, v6
	v_bitop3_b32 v5, v4, v239, 10 bitop3:0x1e
	v_lshl_add_u32 v61, v5, 4, v6
	v_bitop3_b32 v5, v4, v239, 12 bitop3:0x1e
	v_bitop3_b32 v4, v4, v239, 14 bitop3:0x1e
	v_lshl_add_u32 v65, v5, 4, v6
	v_lshl_add_u32 v66, v4, 4, v6
	ds_read_b128 v[24:27], v53
	ds_read_b128 v[4:7], v53 offset:8192
	ds_read_b128 v[32:35], v57
	ds_read_b128 v[8:11], v57 offset:8192
	ds_read_b128 v[36:39], v61
	ds_read_b128 v[12:15], v61 offset:8192
	ds_read_b128 v[40:43], v66
	ds_read_b128 v[16:19], v66 offset:8192
	ds_read_b128 v[44:47], v52 offset:8192
	ds_read_b128 v[20:23], v52 offset:16384
	ds_read_b128 v[128:131], v56 offset:8192
	ds_read_b128 v[28:31], v56 offset:16384
	ds_read_b128 v[136:139], v60 offset:8192
	ds_read_b128 v[108:111], v60 offset:16384
	ds_read_b128 v[144:147], v65 offset:8192
	ds_read_b128 v[112:115], v65 offset:16384
	ds_read_b128 v[148:151], v53 offset:16384
	ds_read_b128 v[116:119], v53 offset:24576
	ds_read_b128 v[160:163], v57 offset:16384
	ds_read_b128 v[120:123], v57 offset:24576
	ds_read_b128 v[168:171], v61 offset:16384
	ds_read_b128 v[124:127], v61 offset:24576
	ds_read_b128 v[176:179], v66 offset:16384
	ds_read_b128 v[132:135], v66 offset:24576
	ds_read_b128 v[48:51], v52
	ds_read_b128 v[140:143], v52 offset:32768
	ds_read_b128 v[192:195], v52 offset:24576
	ds_read_b128 v[152:155], v53 offset:32768
	ds_read_b128 v[52:55], v56
	ds_read_b128 v[156:159], v56 offset:32768
	ds_read_b128 v[196:199], v56 offset:24576
	ds_read_b128 v[164:167], v57 offset:32768
	ds_read_b128 v[56:59], v60
	ds_read_b128 v[172:175], v60 offset:32768
	ds_read_b128 v[200:203], v60 offset:24576
	ds_read_b128 v[180:183], v61 offset:32768
	ds_read_b128 v[60:63], v65
	ds_read_b128 v[184:187], v65 offset:32768
	ds_read_b128 v[204:207], v65 offset:24576
	ds_read_b128 v[188:191], v66 offset:32768
	s_sub_i32 s27, s27, 64
	v_lshlrev_b32_e32 v64, 3, v239
	s_waitcnt vmcnt(0) lgkmcnt(0)
	v_bfe_u32 v65, v237, 2, 3
	v_or3_b32 v64, v65, s27, v64
	v_lshlrev_b32_e32 v65, 3, v237
	v_lshrrev_b32_e32 v221, 2, v237
	v_and_b32_e32 v212, 24, v65
	s_mov_b32 s29, 0
	s_waitcnt lgkmcnt(0)
	s_barrier
